# first queue fetch goes straight to the own-XCD counter (no 8-counter scan on the first fetch)
# baseline (speedup 1.0000x reference)
.Lq_init:
	s_add_u32 s90, s54, 0x80000
	s_addc_u32 s91, s55, 0
	s_getreg_b32 s92, hwreg(HW_REG_XCC_ID, 0, 4)
	s_and_b32 s92, s92, 7
	s_mov_b32 s93, 1
.Lq_fetch:
	v_readfirstlane_b32 s96, v255
	s_cmp_lg_u32 s96, 0
	s_cbranch_scc1 .Lq_f1
	s_mov_b64 s[96:97], exec
	s_cmp_eq_u32 s93, 1
	s_mov_b32 s93, 0
	s_cbranch_scc1 .Lq_take
.Lq_scan:
	s_mov_b64 exec, 0xff
	v_mbcnt_lo_u32_b32 v251, -1, 0
	v_lshlrev_b32_e32 v251, 6, v251
	global_load_dword v250, v251, s[90:91] sc1
	s_waitcnt vmcnt(0)
	v_cmp_gt_u32_e32 vcc, 0x80, v250
	s_mov_b32 s95, vcc_lo
	s_cmp_eq_u32 s95, 0
	s_cbranch_scc1 .Lq_none
	s_lshr_b32 s94, s95, s92
	s_lshl_b32 s94, s94, s92
	s_cmp_lg_u32 s94, 0
	s_cselect_b32 s95, s94, s95
	s_ff1_i32_b32 s92, s95
.Lq_take:
	s_mov_b64 exec, 1
	v_mov_b32_e32 v250, 1
	s_lshl_b32 s95, s92, 6
	v_mov_b32_e32 v251, s95
	global_atomic_add v250, v251, v250, s[90:91] sc0
	s_waitcnt vmcnt(0)
	v_readfirstlane_b32 s95, v250
	s_cmp_ge_u32 s95, 0x80
	s_cbranch_scc1 .Lq_scan
	s_lshl_b32 s94, s92, 8
	s_or_b32 s95, s95, s94
	s_branch .Lq_pub
